# attnC compute block rescheduled by hand (QK read ring, bfe/and masking, V-fragment reads issued ahead into freed score registers, counted waits)
# speedup vs baseline: 1.0428x; 1.0011x over previous
.LBB0_1057:
	v_cmp_le_i32_e32 vcc, s12, v187
	s_and_saveexec_b64 s[10:11], vcc
	s_cbranch_execz .LBB0_1059
	s_lshl_b32 s12, s12, 15
	s_and_b32 s12, s12, 0x8000
	s_add_i32 s12, s80, s12
	v_add3_u32 v220, s12, v186, v190
	v_add_u32_e32 v221, v220, v199
	v_add_u32_e32 v222, v220, v200
	v_add_u32_e32 v223, v220, v201
	v_add_u32_e32 v224, v220, v202
	v_add_u32_e32 v225, v220, v203
	v_add_u32_e32 v226, v220, v216
	v_add_u32_e32 v227, v220, v217
	v_add_u32_e32 v228, v220, v218
	v_lshrrev_b32_e32 v229, v189, v168
	v_lshrrev_b32_e32 v230, v189, v169
	v_add3_u32 v0, s12, v191, v188
	ds_read_b128 v[2:5], v0
	ds_read_b128 v[8:11], v0 offset:8192
	v_add3_u32 v0, s12, v192, v188
	ds_read_b128 v[12:15], v0
	s_waitcnt lgkmcnt(2)
	v_mfma_f32_32x32x16_bf16 v[112:127], v[2:5], v[156:159], v[16:31]
	ds_read_b128 v[2:5], v0 offset:8192
	s_waitcnt lgkmcnt(2)
	v_mfma_f32_32x32x16_bf16 v[96:111], v[8:11], v[156:159], v[16:31]
	v_add3_u32 v0, s12, v193, v188
	ds_read_b128 v[8:11], v0
	s_waitcnt lgkmcnt(2)
	v_mfma_f32_32x32x16_bf16 v[112:127], v[12:15], v[128:131], v[112:127]
	ds_read_b128 v[12:15], v0 offset:8192
	s_waitcnt lgkmcnt(2)
	v_mfma_f32_32x32x16_bf16 v[96:111], v[2:5], v[128:131], v[96:111]
	v_add3_u32 v0, s12, v194, v188
	ds_read_b128 v[2:5], v0
	s_waitcnt lgkmcnt(2)
	v_mfma_f32_32x32x16_bf16 v[112:127], v[8:11], v[132:135], v[112:127]
	ds_read_b128 v[8:11], v0 offset:8192
	s_waitcnt lgkmcnt(2)
	v_mfma_f32_32x32x16_bf16 v[96:111], v[12:15], v[132:135], v[96:111]
	v_add3_u32 v0, s12, v195, v188
	ds_read_b128 v[12:15], v0
	s_waitcnt lgkmcnt(2)
	v_mfma_f32_32x32x16_bf16 v[112:127], v[2:5], v[136:139], v[112:127]
	ds_read_b128 v[2:5], v0 offset:8192
	s_waitcnt lgkmcnt(2)
	v_mfma_f32_32x32x16_bf16 v[96:111], v[8:11], v[136:139], v[96:111]
	v_add3_u32 v0, s12, v196, v188
	ds_read_b128 v[8:11], v0
	s_waitcnt lgkmcnt(2)
	v_mfma_f32_32x32x16_bf16 v[112:127], v[12:15], v[140:143], v[112:127]
	ds_read_b128 v[12:15], v0 offset:8192
	s_waitcnt lgkmcnt(2)
	v_mfma_f32_32x32x16_bf16 v[96:111], v[2:5], v[140:143], v[96:111]
	v_add3_u32 v0, s12, v197, v188
	ds_read_b128 v[2:5], v0
	s_waitcnt lgkmcnt(2)
	v_mfma_f32_32x32x16_bf16 v[112:127], v[8:11], v[144:147], v[112:127]
	ds_read_b128 v[8:11], v0 offset:8192
	s_waitcnt lgkmcnt(2)
	v_mfma_f32_32x32x16_bf16 v[96:111], v[12:15], v[144:147], v[96:111]
	v_add3_u32 v0, s12, v198, v188
	ds_read_b128 v[12:15], v0
	s_waitcnt lgkmcnt(2)
	v_mfma_f32_32x32x16_bf16 v[112:127], v[2:5], v[148:151], v[112:127]
	ds_read_b128 v[2:5], v0 offset:8192
	s_waitcnt lgkmcnt(2)
	v_mfma_f32_32x32x16_bf16 v[96:111], v[8:11], v[148:151], v[96:111]
	s_waitcnt lgkmcnt(1)
	v_mfma_f32_32x32x16_bf16 v[112:127], v[12:15], v[152:155], v[112:127]
	s_waitcnt lgkmcnt(0)
	v_mfma_f32_32x32x16_bf16 v[96:111], v[2:5], v[152:155], v[96:111]
	ds_read_b64 v[8:9], v221 offset:16384
	ds_read_b64 v[10:11], v222 offset:16384
	ds_read_b64 v[12:13], v221 offset:20480
	ds_read_b64 v[14:15], v222 offset:20480
	ds_read_b64 v[236:237], v221 offset:28672
	ds_read_b64 v[238:239], v222 offset:28672
	s_nop 3
	v_exp_f32_e32 v112, v112
	v_exp_f32_e32 v113, v113
	v_exp_f32_e32 v114, v114
	v_exp_f32_e32 v115, v115
	v_exp_f32_e32 v116, v116
	v_exp_f32_e32 v117, v117
	v_exp_f32_e32 v118, v118
	v_exp_f32_e32 v119, v119
	v_bfe_i32 v231, v229, 0, 1
	v_and_b32_e32 v112, v112, v231
	v_bfe_i32 v232, v229, 1, 1
	v_and_b32_e32 v113, v113, v232
	v_bfe_i32 v231, v229, 2, 1
	v_and_b32_e32 v114, v114, v231
	v_bfe_i32 v232, v229, 3, 1
	v_and_b32_e32 v115, v115, v232
	v_bfe_i32 v231, v229, 8, 1
	v_and_b32_e32 v116, v116, v231
	v_bfe_i32 v232, v229, 9, 1
	v_and_b32_e32 v117, v117, v232
	v_bfe_i32 v231, v229, 10, 1
	v_and_b32_e32 v118, v118, v231
	v_bfe_i32 v232, v229, 11, 1
	v_and_b32_e32 v119, v119, v232
	v_cvt_pk_bf16_f32 v2, v112, v113
	v_cvt_pk_bf16_f32 v3, v114, v115
	v_cvt_pk_bf16_f32 v4, v116, v117
	v_cvt_pk_bf16_f32 v5, v118, v119
	v_add_f32_e32 v0, 0, v112
	v_add_f32_e32 v0, v113, v0
	v_add_f32_e32 v0, v114, v0
	v_add_f32_e32 v0, v115, v0
	v_add_f32_e32 v0, v116, v0
	v_add_f32_e32 v0, v117, v0
	v_add_f32_e32 v0, v118, v0
	v_add_f32_e32 v0, v119, v0
	ds_read_b64 v[240:241], v221 offset:24576
	ds_read_b64 v[242:243], v222 offset:24576
	ds_read_b64 v[244:245], v223 offset:16384
	ds_read_b64 v[246:247], v224 offset:16384
	s_waitcnt lgkmcnt(8)
	v_mfma_f32_32x32x16_bf16 v[80:95], v[8:11], v[2:5], v[80:95]
	ds_read_b64 v[112:113], v223 offset:20480
	ds_read_b64 v[114:115], v224 offset:20480
	v_exp_f32_e32 v120, v120
	v_exp_f32_e32 v121, v121
	s_waitcnt lgkmcnt(8)
	v_mfma_f32_32x32x16_bf16 v[64:79], v[12:15], v[2:5], v[64:79]
	ds_read_b64 v[116:117], v223 offset:24576
	ds_read_b64 v[118:119], v224 offset:24576
	v_exp_f32_e32 v122, v122
	v_exp_f32_e32 v123, v123
	v_bfe_i32 v231, v229, 16, 1
	v_and_b32_e32 v120, v120, v231
	v_bfe_i32 v232, v229, 17, 1
	v_and_b32_e32 v121, v121, v232
	v_add_f32_e32 v0, v120, v0
	v_add_f32_e32 v0, v121, v0
	s_waitcnt lgkmcnt(8)
	v_mfma_f32_32x32x16_bf16 v[32:47], v[236:239], v[2:5], v[32:47]
	ds_read_b64 v[8:9], v223 offset:28672
	ds_read_b64 v[10:11], v224 offset:28672
	v_exp_f32_e32 v124, v124
	v_exp_f32_e32 v125, v125
	v_bfe_i32 v231, v229, 18, 1
	v_and_b32_e32 v122, v122, v231
	v_bfe_i32 v232, v229, 19, 1
	v_and_b32_e32 v123, v123, v232
	v_add_f32_e32 v0, v122, v0
	v_add_f32_e32 v0, v123, v0
	s_waitcnt lgkmcnt(8)
	v_mfma_f32_32x32x16_bf16 v[48:63], v[240:243], v[2:5], v[48:63]
	ds_read_b64 v[12:13], v225 offset:16384
	ds_read_b64 v[14:15], v226 offset:16384
	v_exp_f32_e32 v126, v126
	v_exp_f32_e32 v127, v127
	v_bfe_i32 v231, v229, 24, 1
	v_and_b32_e32 v124, v124, v231
	v_bfe_i32 v232, v229, 25, 1
	v_and_b32_e32 v125, v125, v232
	v_add_f32_e32 v0, v124, v0
	v_add_f32_e32 v0, v125, v0
	v_bfe_i32 v231, v229, 26, 1
	v_and_b32_e32 v126, v126, v231
	v_bfe_i32 v232, v229, 27, 1
	v_and_b32_e32 v127, v127, v232
	v_add_f32_e32 v0, v126, v0
	v_add_f32_e32 v0, v127, v0
	v_cvt_pk_bf16_f32 v2, v120, v121
	v_cvt_pk_bf16_f32 v3, v122, v123
	v_cvt_pk_bf16_f32 v4, v124, v125
	v_cvt_pk_bf16_f32 v5, v126, v127
	s_nop 1
	ds_read_b64 v[236:237], v225 offset:20480
	ds_read_b64 v[238:239], v226 offset:20480
	s_waitcnt lgkmcnt(10)
	v_mfma_f32_32x32x16_bf16 v[80:95], v[244:247], v[2:5], v[80:95]
	ds_read_b64 v[240:241], v225 offset:24576
	ds_read_b64 v[242:243], v226 offset:24576
	v_exp_f32_e32 v96, v96
	v_exp_f32_e32 v97, v97
	s_waitcnt lgkmcnt(10)
	v_mfma_f32_32x32x16_bf16 v[64:79], v[112:115], v[2:5], v[64:79]
	ds_read_b64 v[120:121], v225 offset:28672
	ds_read_b64 v[122:123], v226 offset:28672
	v_exp_f32_e32 v98, v98
	v_exp_f32_e32 v99, v99
	v_bfe_i32 v231, v230, 0, 1
	v_and_b32_e32 v96, v96, v231
	v_bfe_i32 v232, v230, 1, 1
	v_and_b32_e32 v97, v97, v232
	v_add_f32_e32 v0, v96, v0
	v_add_f32_e32 v0, v97, v0
	s_waitcnt lgkmcnt(10)
	v_mfma_f32_32x32x16_bf16 v[48:63], v[116:119], v[2:5], v[48:63]
	ds_read_b64 v[124:125], v227 offset:16384
	ds_read_b64 v[126:127], v228 offset:16384
	v_exp_f32_e32 v100, v100
	v_exp_f32_e32 v101, v101
	v_bfe_i32 v231, v230, 2, 1
	v_and_b32_e32 v98, v98, v231
	v_bfe_i32 v232, v230, 3, 1
	v_and_b32_e32 v99, v99, v232
	v_add_f32_e32 v0, v98, v0
	v_add_f32_e32 v0, v99, v0
	s_waitcnt lgkmcnt(10)
	v_mfma_f32_32x32x16_bf16 v[32:47], v[8:11], v[2:5], v[32:47]
	ds_read_b64 v[244:245], v227 offset:20480
	ds_read_b64 v[246:247], v228 offset:20480
	v_exp_f32_e32 v102, v102
	v_exp_f32_e32 v103, v103
	v_bfe_i32 v231, v230, 8, 1
	v_and_b32_e32 v100, v100, v231
	v_bfe_i32 v232, v230, 9, 1
	v_and_b32_e32 v101, v101, v232
	v_add_f32_e32 v0, v100, v0
	v_add_f32_e32 v0, v101, v0
	v_bfe_i32 v231, v230, 10, 1
	v_and_b32_e32 v102, v102, v231
	v_bfe_i32 v232, v230, 11, 1
	v_and_b32_e32 v103, v103, v232
	v_add_f32_e32 v0, v102, v0
	v_add_f32_e32 v0, v103, v0
	v_cvt_pk_bf16_f32 v2, v96, v97
	v_cvt_pk_bf16_f32 v3, v98, v99
	v_cvt_pk_bf16_f32 v4, v100, v101
	v_cvt_pk_bf16_f32 v5, v102, v103
	s_nop 1
	ds_read_b64 v[112:113], v227 offset:24576
	ds_read_b64 v[114:115], v228 offset:24576
	s_waitcnt lgkmcnt(12)
	v_mfma_f32_32x32x16_bf16 v[80:95], v[12:15], v[2:5], v[80:95]
	ds_read_b64 v[116:117], v227 offset:28672
	ds_read_b64 v[118:119], v228 offset:28672
	v_exp_f32_e32 v104, v104
	v_exp_f32_e32 v105, v105
	s_waitcnt lgkmcnt(12)
	v_mfma_f32_32x32x16_bf16 v[64:79], v[236:239], v[2:5], v[64:79]
	v_exp_f32_e32 v106, v106
	v_exp_f32_e32 v107, v107
	v_bfe_i32 v231, v230, 16, 1
	v_and_b32_e32 v104, v104, v231
	v_bfe_i32 v232, v230, 17, 1
	v_and_b32_e32 v105, v105, v232
	v_add_f32_e32 v0, v104, v0
	v_add_f32_e32 v0, v105, v0
	s_waitcnt lgkmcnt(10)
	v_mfma_f32_32x32x16_bf16 v[48:63], v[240:243], v[2:5], v[48:63]
	v_exp_f32_e32 v108, v108
	v_exp_f32_e32 v109, v109
	v_bfe_i32 v231, v230, 18, 1
	v_and_b32_e32 v106, v106, v231
	v_bfe_i32 v232, v230, 19, 1
	v_and_b32_e32 v107, v107, v232
	v_add_f32_e32 v0, v106, v0
	v_add_f32_e32 v0, v107, v0
	s_waitcnt lgkmcnt(8)
	v_mfma_f32_32x32x16_bf16 v[32:47], v[120:123], v[2:5], v[32:47]
	v_exp_f32_e32 v110, v110
	v_exp_f32_e32 v111, v111
	v_bfe_i32 v231, v230, 24, 1
	v_and_b32_e32 v108, v108, v231
	v_bfe_i32 v232, v230, 25, 1
	v_and_b32_e32 v109, v109, v232
	v_add_f32_e32 v0, v108, v0
	v_add_f32_e32 v0, v109, v0
	v_bfe_i32 v231, v230, 26, 1
	v_and_b32_e32 v110, v110, v231
	v_bfe_i32 v232, v230, 27, 1
	v_and_b32_e32 v111, v111, v232
	v_add_f32_e32 v0, v110, v0
	v_add_f32_e32 v0, v111, v0
	v_cvt_pk_bf16_f32 v2, v104, v105
	v_cvt_pk_bf16_f32 v3, v106, v107
	v_cvt_pk_bf16_f32 v4, v108, v109
	v_cvt_pk_bf16_f32 v5, v110, v111
	s_nop 1
	s_waitcnt lgkmcnt(6)
	v_mfma_f32_32x32x16_bf16 v[80:95], v[124:127], v[2:5], v[80:95]
	s_waitcnt lgkmcnt(4)
	v_mfma_f32_32x32x16_bf16 v[64:79], v[244:247], v[2:5], v[64:79]
	s_waitcnt lgkmcnt(2)
	v_mfma_f32_32x32x16_bf16 v[48:63], v[112:115], v[2:5], v[48:63]
	s_waitcnt lgkmcnt(0)
	v_mfma_f32_32x32x16_bf16 v[32:47], v[116:119], v[2:5], v[32:47]
	v_add_f32_e32 v219, v219, v0
